# phase-0 GEMV unit: silu(c) staging loop de-serialised (ten loads in flight per thread instead of load-wait-compute-write per iteration)
# speedup vs baseline: 1.0114x; 1.0049x over previous
.LBB0_103:
	v_and_b32_e32 v6, 0x3ff, v5
	v_lshlrev_b32_e32 v62, 2, v6
	v_lshl_add_u64 v[6:7], s[78:79], 0, v[62:63]
	v_cmp_gt_i32_e32 vcc, s62, v5
	s_nop 1
	v_cndmask_b32_e32 v7, v7, v3, vcc
	v_cndmask_b32_e32 v6, v6, v2, vcc
	global_load_dword v200, v[6:7], off
	v_lshl_add_u64 v[2:3], v[2:3], 0, s[22:23]
	v_add_u32_e32 v210, 0x200, v5
	v_and_b32_e32 v6, 0x3ff, v210
	v_lshlrev_b32_e32 v62, 2, v6
	v_lshl_add_u64 v[6:7], s[78:79], 0, v[62:63]
	v_cmp_gt_i32_e32 vcc, s62, v210
	s_nop 1
	v_cndmask_b32_e32 v7, v7, v3, vcc
	v_cndmask_b32_e32 v6, v6, v2, vcc
	global_load_dword v201, v[6:7], off
	v_lshl_add_u64 v[2:3], v[2:3], 0, s[22:23]
	v_add_u32_e32 v210, 0x400, v5
	v_and_b32_e32 v6, 0x3ff, v210
	v_lshlrev_b32_e32 v62, 2, v6
	v_lshl_add_u64 v[6:7], s[78:79], 0, v[62:63]
	v_cmp_gt_i32_e32 vcc, s62, v210
	s_nop 1
	v_cndmask_b32_e32 v7, v7, v3, vcc
	v_cndmask_b32_e32 v6, v6, v2, vcc
	global_load_dword v202, v[6:7], off
	v_lshl_add_u64 v[2:3], v[2:3], 0, s[22:23]
	v_add_u32_e32 v210, 0x600, v5
	v_and_b32_e32 v6, 0x3ff, v210
	v_lshlrev_b32_e32 v62, 2, v6
	v_lshl_add_u64 v[6:7], s[78:79], 0, v[62:63]
	v_cmp_gt_i32_e32 vcc, s62, v210
	s_nop 1
	v_cndmask_b32_e32 v7, v7, v3, vcc
	v_cndmask_b32_e32 v6, v6, v2, vcc
	global_load_dword v203, v[6:7], off
	v_lshl_add_u64 v[2:3], v[2:3], 0, s[22:23]
	v_add_u32_e32 v210, 0x800, v5
	v_and_b32_e32 v6, 0x3ff, v210
	v_lshlrev_b32_e32 v62, 2, v6
	v_lshl_add_u64 v[6:7], s[78:79], 0, v[62:63]
	v_cmp_gt_i32_e32 vcc, s62, v210
	s_nop 1
	v_cndmask_b32_e32 v7, v7, v3, vcc
	v_cndmask_b32_e32 v6, v6, v2, vcc
	global_load_dword v204, v[6:7], off
	v_lshl_add_u64 v[2:3], v[2:3], 0, s[22:23]
	v_add_u32_e32 v210, 0xa00, v5
	v_and_b32_e32 v6, 0x3ff, v210
	v_lshlrev_b32_e32 v62, 2, v6
	v_lshl_add_u64 v[6:7], s[78:79], 0, v[62:63]
	v_cmp_gt_i32_e32 vcc, s62, v210
	s_nop 1
	v_cndmask_b32_e32 v7, v7, v3, vcc
	v_cndmask_b32_e32 v6, v6, v2, vcc
	global_load_dword v205, v[6:7], off
	v_lshl_add_u64 v[2:3], v[2:3], 0, s[22:23]
	v_add_u32_e32 v210, 0xc00, v5
	v_and_b32_e32 v6, 0x3ff, v210
	v_lshlrev_b32_e32 v62, 2, v6
	v_lshl_add_u64 v[6:7], s[78:79], 0, v[62:63]
	v_cmp_gt_i32_e32 vcc, s62, v210
	s_nop 1
	v_cndmask_b32_e32 v7, v7, v3, vcc
	v_cndmask_b32_e32 v6, v6, v2, vcc
	global_load_dword v206, v[6:7], off
	v_lshl_add_u64 v[2:3], v[2:3], 0, s[22:23]
	v_add_u32_e32 v210, 0xe00, v5
	v_and_b32_e32 v6, 0x3ff, v210
	v_lshlrev_b32_e32 v62, 2, v6
	v_lshl_add_u64 v[6:7], s[78:79], 0, v[62:63]
	v_cmp_gt_i32_e32 vcc, s62, v210
	s_nop 1
	v_cndmask_b32_e32 v7, v7, v3, vcc
	v_cndmask_b32_e32 v6, v6, v2, vcc
	global_load_dword v207, v[6:7], off
	v_lshl_add_u64 v[2:3], v[2:3], 0, s[22:23]
	v_add_u32_e32 v210, 0x1000, v5
	v_and_b32_e32 v6, 0x3ff, v210
	v_lshlrev_b32_e32 v62, 2, v6
	v_lshl_add_u64 v[6:7], s[78:79], 0, v[62:63]
	v_cmp_gt_i32_e32 vcc, s62, v210
	s_nop 1
	v_cndmask_b32_e32 v7, v7, v3, vcc
	v_cndmask_b32_e32 v6, v6, v2, vcc
	global_load_dword v208, v[6:7], off
	v_lshl_add_u64 v[2:3], v[2:3], 0, s[22:23]
	v_add_u32_e32 v210, 0x1200, v5
	v_and_b32_e32 v6, 0x3ff, v210
	v_lshlrev_b32_e32 v62, 2, v6
	v_lshl_add_u64 v[6:7], s[78:79], 0, v[62:63]
	v_cmp_gt_i32_e32 vcc, s62, v210
	s_nop 1
	v_cndmask_b32_e32 v7, v7, v3, vcc
	v_cndmask_b32_e32 v6, v6, v2, vcc
	global_load_dword v209, v[6:7], off
	v_lshl_add_u64 v[2:3], v[2:3], 0, s[22:23]
	s_waitcnt vmcnt(9)
	v_mov_b32_e32 v6, v200
	v_mul_f32_e32 v7, 0xbfb8aa3b, v6
	v_exp_f32_e32 v7, v7
	s_nop 0
	v_add_f32_e32 v7, 1.0, v7
	v_div_scale_f32 v8, s[8:9], v7, v7, v6
	v_rcp_f32_e32 v9, v8
	v_div_scale_f32 v10, vcc, v6, v7, v6
	v_fma_f32 v11, -v8, v9, 1.0
	v_fmac_f32_e32 v9, v11, v9
	v_mul_f32_e32 v11, v10, v9
	v_fma_f32 v12, -v8, v11, v10
	v_fmac_f32_e32 v11, v12, v9
	v_fma_f32 v8, -v8, v11, v10
	v_div_fmas_f32 v8, v8, v9, v11
	v_div_fixup_f32 v6, v8, v7, v6
	ds_write_b32 v4, v6
	s_waitcnt vmcnt(8)
	v_mov_b32_e32 v6, v201
	v_mul_f32_e32 v7, 0xbfb8aa3b, v6
	v_exp_f32_e32 v7, v7
	s_nop 0
	v_add_f32_e32 v7, 1.0, v7
	v_div_scale_f32 v8, s[8:9], v7, v7, v6
	v_rcp_f32_e32 v9, v8
	v_div_scale_f32 v10, vcc, v6, v7, v6
	v_fma_f32 v11, -v8, v9, 1.0
	v_fmac_f32_e32 v9, v11, v9
	v_mul_f32_e32 v11, v10, v9
	v_fma_f32 v12, -v8, v11, v10
	v_fmac_f32_e32 v11, v12, v9
	v_fma_f32 v8, -v8, v11, v10
	v_div_fmas_f32 v8, v8, v9, v11
	v_div_fixup_f32 v6, v8, v7, v6
	ds_write_b32 v4, v6 offset:2048
	s_waitcnt vmcnt(7)
	v_mov_b32_e32 v6, v202
	v_mul_f32_e32 v7, 0xbfb8aa3b, v6
	v_exp_f32_e32 v7, v7
	s_nop 0
	v_add_f32_e32 v7, 1.0, v7
	v_div_scale_f32 v8, s[8:9], v7, v7, v6
	v_rcp_f32_e32 v9, v8
	v_div_scale_f32 v10, vcc, v6, v7, v6
	v_fma_f32 v11, -v8, v9, 1.0
	v_fmac_f32_e32 v9, v11, v9
	v_mul_f32_e32 v11, v10, v9
	v_fma_f32 v12, -v8, v11, v10
	v_fmac_f32_e32 v11, v12, v9
	v_fma_f32 v8, -v8, v11, v10
	v_div_fmas_f32 v8, v8, v9, v11
	v_div_fixup_f32 v6, v8, v7, v6
	ds_write_b32 v4, v6 offset:4096
	s_waitcnt vmcnt(6)
	v_mov_b32_e32 v6, v203
	v_mul_f32_e32 v7, 0xbfb8aa3b, v6
	v_exp_f32_e32 v7, v7
	s_nop 0
	v_add_f32_e32 v7, 1.0, v7
	v_div_scale_f32 v8, s[8:9], v7, v7, v6
	v_rcp_f32_e32 v9, v8
	v_div_scale_f32 v10, vcc, v6, v7, v6
	v_fma_f32 v11, -v8, v9, 1.0
	v_fmac_f32_e32 v9, v11, v9
	v_mul_f32_e32 v11, v10, v9
	v_fma_f32 v12, -v8, v11, v10
	v_fmac_f32_e32 v11, v12, v9
	v_fma_f32 v8, -v8, v11, v10
	v_div_fmas_f32 v8, v8, v9, v11
	v_div_fixup_f32 v6, v8, v7, v6
	ds_write_b32 v4, v6 offset:6144
	s_waitcnt vmcnt(5)
	v_mov_b32_e32 v6, v204
	v_mul_f32_e32 v7, 0xbfb8aa3b, v6
	v_exp_f32_e32 v7, v7
	s_nop 0
	v_add_f32_e32 v7, 1.0, v7
	v_div_scale_f32 v8, s[8:9], v7, v7, v6
	v_rcp_f32_e32 v9, v8
	v_div_scale_f32 v10, vcc, v6, v7, v6
	v_fma_f32 v11, -v8, v9, 1.0
	v_fmac_f32_e32 v9, v11, v9
	v_mul_f32_e32 v11, v10, v9
	v_fma_f32 v12, -v8, v11, v10
	v_fmac_f32_e32 v11, v12, v9
	v_fma_f32 v8, -v8, v11, v10
	v_div_fmas_f32 v8, v8, v9, v11
	v_div_fixup_f32 v6, v8, v7, v6
	ds_write_b32 v4, v6 offset:8192
	s_waitcnt vmcnt(4)
	v_mov_b32_e32 v6, v205
	v_mul_f32_e32 v7, 0xbfb8aa3b, v6
	v_exp_f32_e32 v7, v7
	s_nop 0
	v_add_f32_e32 v7, 1.0, v7
	v_div_scale_f32 v8, s[8:9], v7, v7, v6
	v_rcp_f32_e32 v9, v8
	v_div_scale_f32 v10, vcc, v6, v7, v6
	v_fma_f32 v11, -v8, v9, 1.0
	v_fmac_f32_e32 v9, v11, v9
	v_mul_f32_e32 v11, v10, v9
	v_fma_f32 v12, -v8, v11, v10
	v_fmac_f32_e32 v11, v12, v9
	v_fma_f32 v8, -v8, v11, v10
	v_div_fmas_f32 v8, v8, v9, v11
	v_div_fixup_f32 v6, v8, v7, v6
	ds_write_b32 v4, v6 offset:10240
	s_waitcnt vmcnt(3)
	v_mov_b32_e32 v6, v206
	v_mul_f32_e32 v7, 0xbfb8aa3b, v6
	v_exp_f32_e32 v7, v7
	s_nop 0
	v_add_f32_e32 v7, 1.0, v7
	v_div_scale_f32 v8, s[8:9], v7, v7, v6
	v_rcp_f32_e32 v9, v8
	v_div_scale_f32 v10, vcc, v6, v7, v6
	v_fma_f32 v11, -v8, v9, 1.0
	v_fmac_f32_e32 v9, v11, v9
	v_mul_f32_e32 v11, v10, v9
	v_fma_f32 v12, -v8, v11, v10
	v_fmac_f32_e32 v11, v12, v9
	v_fma_f32 v8, -v8, v11, v10
	v_div_fmas_f32 v8, v8, v9, v11
	v_div_fixup_f32 v6, v8, v7, v6
	ds_write_b32 v4, v6 offset:12288
	s_waitcnt vmcnt(2)
	v_mov_b32_e32 v6, v207
	v_mul_f32_e32 v7, 0xbfb8aa3b, v6
	v_exp_f32_e32 v7, v7
	s_nop 0
	v_add_f32_e32 v7, 1.0, v7
	v_div_scale_f32 v8, s[8:9], v7, v7, v6
	v_rcp_f32_e32 v9, v8
	v_div_scale_f32 v10, vcc, v6, v7, v6
	v_fma_f32 v11, -v8, v9, 1.0
	v_fmac_f32_e32 v9, v11, v9
	v_mul_f32_e32 v11, v10, v9
	v_fma_f32 v12, -v8, v11, v10
	v_fmac_f32_e32 v11, v12, v9
	v_fma_f32 v8, -v8, v11, v10
	v_div_fmas_f32 v8, v8, v9, v11
	v_div_fixup_f32 v6, v8, v7, v6
	ds_write_b32 v4, v6 offset:14336
	s_waitcnt vmcnt(1)
	v_mov_b32_e32 v6, v208
	v_mul_f32_e32 v7, 0xbfb8aa3b, v6
	v_exp_f32_e32 v7, v7
	s_nop 0
	v_add_f32_e32 v7, 1.0, v7
	v_div_scale_f32 v8, s[8:9], v7, v7, v6
	v_rcp_f32_e32 v9, v8
	v_div_scale_f32 v10, vcc, v6, v7, v6
	v_fma_f32 v11, -v8, v9, 1.0
	v_fmac_f32_e32 v9, v11, v9
	v_mul_f32_e32 v11, v10, v9
	v_fma_f32 v12, -v8, v11, v10
	v_fmac_f32_e32 v11, v12, v9
	v_fma_f32 v8, -v8, v11, v10
	v_div_fmas_f32 v8, v8, v9, v11
	v_div_fixup_f32 v6, v8, v7, v6
	ds_write_b32 v4, v6 offset:16384
	s_waitcnt vmcnt(0)
	v_mov_b32_e32 v6, v209
	v_mul_f32_e32 v7, 0xbfb8aa3b, v6
	v_exp_f32_e32 v7, v7
	s_nop 0
	v_add_f32_e32 v7, 1.0, v7
	v_div_scale_f32 v8, s[8:9], v7, v7, v6
	v_rcp_f32_e32 v9, v8
	v_div_scale_f32 v10, vcc, v6, v7, v6
	v_fma_f32 v11, -v8, v9, 1.0
	v_fmac_f32_e32 v9, v11, v9
	v_mul_f32_e32 v11, v10, v9
	v_fma_f32 v12, -v8, v11, v10
	v_fmac_f32_e32 v11, v12, v9
	v_fma_f32 v8, -v8, v11, v10
	v_div_fmas_f32 v8, v8, v9, v11
	v_div_fixup_f32 v6, v8, v7, v6
	ds_write_b32 v4, v6 offset:18432
